# adds: attention loop near-diagonal ALiBi init blocks moved out of line; far-tile path falls through without taken branches
# baseline (speedup 1.0000x reference)
.LBB0_661:
	v_add_u32_e32 v135, s33, v225
	v_add_u32_e32 v0, 31, v135
	s_add_i32 s2, s33, 31
	v_cvt_f32_i32_e32 v82, v0
	s_cmpk_lt_i32 s2, 0xffc2
	s_cselect_b64 s[44:45], -1, 0
	s_cmp_gt_u32 s33, 0xffffffa2
	s_cselect_b64 s[2:3], -1, 0
	s_cmp_lt_u32 s33, 0xffffffa3
	s_mov_b64 s[46:47], -1
	s_cbranch_scc0 .Lnear_a0
	v_cndmask_b32_e64 v0, -v210, v210, s[44:45]
	v_fma_f32 v80, v0, v82, -v209
	v_fma_f32 v66, 0, v0, v80
	v_add_f32_e32 v67, v0, v80
	v_pk_fma_f32 v[68:69], v[0:1], s[6:7], v[80:81] op_sel_hi:[0,1,0]
	v_pk_fma_f32 v[70:71], v[0:1], s[8:9], v[80:81] op_sel_hi:[0,1,0]
	v_pk_fma_f32 v[72:73], v[0:1], s[10:11], v[80:81] op_sel_hi:[0,1,0]
	v_pk_fma_f32 v[74:75], v[0:1], s[12:13], v[80:81] op_sel_hi:[0,1,0]
	v_pk_fma_f32 v[76:77], v[0:1], s[14:15], v[80:81] op_sel_hi:[0,1,0]
	v_pk_fma_f32 v[78:79], v[0:1], s[16:17], v[80:81] op_sel_hi:[0,1,0]
	v_pk_fma_f32 v[80:81], v[0:1], s[18:19], v[80:81] op_sel_hi:[0,1,0]
.LBB0_665:
	v_add_u32_e32 v82, 63, v135
	v_cvt_f32_i32_e32 v114, v82
	s_and_b64 vcc, exec, s[2:3]
	s_cbranch_vccnz .Lnear_a1
	v_fma_f32 v96, v0, v114, -v209
	v_fma_f32 v82, 0, v0, v96
	v_add_f32_e32 v83, v0, v96
	v_pk_fma_f32 v[84:85], v[0:1], s[6:7], v[96:97] op_sel_hi:[0,1,0]
	v_pk_fma_f32 v[86:87], v[0:1], s[8:9], v[96:97] op_sel_hi:[0,1,0]
	v_pk_fma_f32 v[88:89], v[0:1], s[10:11], v[96:97] op_sel_hi:[0,1,0]
	v_pk_fma_f32 v[90:91], v[0:1], s[12:13], v[96:97] op_sel_hi:[0,1,0]
	v_pk_fma_f32 v[92:93], v[0:1], s[14:15], v[96:97] op_sel_hi:[0,1,0]
	v_pk_fma_f32 v[94:95], v[0:1], s[16:17], v[96:97] op_sel_hi:[0,1,0]
	v_pk_fma_f32 v[96:97], v[0:1], s[18:19], v[96:97] op_sel_hi:[0,1,0]
.LBB0_669:
	s_add_i32 s46, s59, 0
	v_add_u32_e32 v173, s46, v212
	s_add_i32 s2, s33, 0x5f
	v_add_u32_e32 v0, 0x5f, v135
	v_add_u32_e32 v235, s46, v222
	ds_read_b128 v[118:121], v173
	v_add_u32_e32 v236, s46, v223
	v_add_u32_e32 v237, s46, v224
	v_cvt_f32_i32_e32 v134, v0
	s_cmpk_lt_i32 s2, 0xffc2
	ds_read_b128 v[136:139], v235
	ds_read_b128 v[140:143], v236
	ds_read_b128 v[144:147], v237
	s_cselect_b64 s[44:45], -1, 0
	s_add_i32 s47, s33, 64
	s_cmp_gt_u32 s47, 0xffffffa2
	s_cselect_b64 s[2:3], -1, 0
	v_add_u32_e32 v230, s46, v213
	v_add_u32_e32 v229, s46, v214
	v_add_u32_e32 v228, s46, v216
	v_add_u32_e32 v227, s46, v217
	v_add_u32_e32 v234, s46, v218
	v_add_u32_e32 v233, s46, v219
	v_add_u32_e32 v232, s46, v220
	v_add_u32_e32 v231, s46, v221
	s_cmp_lt_u32 s47, 0xffffffa3
	s_waitcnt lgkmcnt(0)
	v_mfma_f32_32x32x16_bf16 v[66:81], v[118:121], v[98:101], v[66:81]
	ds_read_b64_tr_b16 v[130:131], v230 offset:0
	ds_read_b64_tr_b16 v[132:133], v229 offset:0
	ds_read_b64_tr_b16 v[126:127], v228 offset:0
	ds_read_b64_tr_b16 v[128:129], v227 offset:0
	ds_read_b64_tr_b16 v[122:123], v234 offset:0
	ds_read_b64_tr_b16 v[124:125], v233 offset:0
	ds_read_b64_tr_b16 v[114:115], v232 offset:0
	v_mfma_f32_32x32x16_bf16 v[66:81], v[136:139], v[102:105], v[66:81]
	ds_read_b64_tr_b16 v[116:117], v231 offset:0
	ds_read_b128 v[118:121], v173 offset:8192
	ds_read_b128 v[136:139], v235 offset:8192
	ds_read_b128 v[194:197], v237 offset:8192
	v_mfma_f32_32x32x16_bf16 v[66:81], v[140:143], v[106:109], v[66:81]
	ds_read_b128 v[140:143], v236 offset:8192
	v_mfma_f32_32x32x16_bf16 v[66:81], v[144:147], v[110:113], v[66:81]
	s_waitcnt lgkmcnt(0)
	v_mfma_f32_32x32x16_bf16 v[82:97], v[118:121], v[98:101], v[82:97]
	s_nop 9
	v_exp_f32_e32 v156, v66
	v_exp_f32_e32 v157, v67
	v_exp_f32_e32 v158, v68
	v_exp_f32_e32 v159, v69
	v_exp_f32_e32 v162, v70
	v_exp_f32_e32 v163, v71
	v_exp_f32_e32 v166, v72
	v_mfma_f32_32x32x16_bf16 v[82:97], v[136:139], v[102:105], v[82:97]
	v_exp_f32_e32 v167, v73
	v_exp_f32_e32 v160, v74
	v_exp_f32_e32 v161, v75
	v_exp_f32_e32 v164, v76
	v_exp_f32_e32 v165, v77
	v_exp_f32_e32 v168, v78
	v_exp_f32_e32 v169, v79
	v_mfma_f32_32x32x16_bf16 v[82:97], v[140:143], v[106:109], v[82:97]
	v_exp_f32_e32 v170, v80
	v_exp_f32_e32 v171, v81
	v_cvt_pk_bf16_f32 v150, v156, v157
	v_cvt_pk_bf16_f32 v151, v158, v159
	v_cvt_pk_bf16_f32 v152, v162, v163
	v_cvt_pk_bf16_f32 v153, v166, v167
	v_cvt_pk_bf16_f32 v118, v160, v161
	v_mfma_f32_32x32x16_bf16 v[82:97], v[194:197], v[110:113], v[82:97]
	v_cvt_pk_bf16_f32 v119, v164, v165
	v_cvt_pk_bf16_f32 v120, v168, v169
	v_cvt_pk_bf16_f32 v121, v170, v171
	s_mov_b64 s[46:47], -1
	s_cbranch_scc0 .Lnear_b0
	v_cndmask_b32_e64 v0, -v210, v210, s[44:45]
	v_fma_f32 v80, v0, v134, -v209
	v_fma_f32 v66, 0, v0, v80
	v_add_f32_e32 v67, v0, v80
	v_pk_fma_f32 v[68:69], v[0:1], s[6:7], v[80:81] op_sel_hi:[0,1,0]
	v_pk_fma_f32 v[70:71], v[0:1], s[8:9], v[80:81] op_sel_hi:[0,1,0]
	v_pk_fma_f32 v[72:73], v[0:1], s[10:11], v[80:81] op_sel_hi:[0,1,0]
	v_pk_fma_f32 v[74:75], v[0:1], s[12:13], v[80:81] op_sel_hi:[0,1,0]
	v_pk_fma_f32 v[76:77], v[0:1], s[14:15], v[80:81] op_sel_hi:[0,1,0]
	v_pk_fma_f32 v[78:79], v[0:1], s[16:17], v[80:81] op_sel_hi:[0,1,0]
	v_pk_fma_f32 v[80:81], v[0:1], s[18:19], v[80:81] op_sel_hi:[0,1,0]

.Ldma_skip_0:
	s_cmp_lg_u32 s85, 0
	s_and_b64 vcc, exec, s[2:3]
	s_cbranch_vccnz .Lnear_b1
	v_fma_f32 v96, v0, v172, -v209
	v_fma_f32 v82, 0, v0, v96
	v_add_f32_e32 v83, v0, v96
	v_pk_fma_f32 v[84:85], v[0:1], s[6:7], v[96:97] op_sel_hi:[0,1,0]
	v_pk_fma_f32 v[86:87], v[0:1], s[8:9], v[96:97] op_sel_hi:[0,1,0]
	v_pk_fma_f32 v[88:89], v[0:1], s[10:11], v[96:97] op_sel_hi:[0,1,0]
	v_pk_fma_f32 v[90:91], v[0:1], s[12:13], v[96:97] op_sel_hi:[0,1,0]
	v_pk_fma_f32 v[92:93], v[0:1], s[14:15], v[96:97] op_sel_hi:[0,1,0]
	v_pk_fma_f32 v[94:95], v[0:1], s[16:17], v[96:97] op_sel_hi:[0,1,0]
	v_pk_fma_f32 v[96:97], v[0:1], s[18:19], v[96:97] op_sel_hi:[0,1,0]
	s_branch .LBB0_656
.Lnear_b1:
	v_add_f32_e32 v96, 1.0, v172
	v_pk_add_f32 v[82:83], v[172:173], s[6:7] op_sel_hi:[0,1]
	v_pk_add_f32 v[84:85], v[172:173], s[8:9] op_sel_hi:[0,1]
	v_pk_add_f32 v[86:87], v[172:173], s[10:11] op_sel_hi:[0,1]
	v_pk_add_f32 v[88:89], v[172:173], s[12:13] op_sel_hi:[0,1]
	v_pk_add_f32 v[90:91], v[172:173], s[14:15] op_sel_hi:[0,1]
	v_pk_add_f32 v[92:93], v[172:173], s[16:17] op_sel_hi:[0,1]
	v_pk_add_f32 v[94:95], v[172:173], s[18:19] op_sel_hi:[0,1]
	v_and_b32_e32 v83, 0x7fffffff, v83
	v_and_b32_e32 v82, 0x7fffffff, v82
	v_and_b32_e32 v85, 0x7fffffff, v85
	v_and_b32_e32 v84, 0x7fffffff, v84
	v_and_b32_e32 v87, 0x7fffffff, v87
	v_and_b32_e32 v86, 0x7fffffff, v86
	v_and_b32_e32 v89, 0x7fffffff, v89
	v_and_b32_e32 v88, 0x7fffffff, v88
	v_and_b32_e32 v91, 0x7fffffff, v91
	v_and_b32_e32 v90, 0x7fffffff, v90
	v_and_b32_e32 v93, 0x7fffffff, v93
	v_and_b32_e32 v92, 0x7fffffff, v92
	v_and_b32_e32 v95, 0x7fffffff, v95
	v_and_b32_e32 v94, 0x7fffffff, v94
	v_and_b32_e32 v238, 0x7fffffff, v172
	v_and_b32_e32 v239, 0x7fffffff, v96
	v_mov_b32_e32 v175, v174
	v_pk_fma_f32 v[96:97], v[94:95], v[174:175], v[192:193]
	v_pk_fma_f32 v[94:95], v[92:93], v[174:175], v[190:191]
	v_pk_fma_f32 v[92:93], v[90:91], v[174:175], v[188:189]
	v_pk_fma_f32 v[90:91], v[88:89], v[174:175], v[186:187]
	v_pk_fma_f32 v[88:89], v[86:87], v[174:175], v[184:185]
	v_pk_fma_f32 v[86:87], v[84:85], v[174:175], v[182:183]
	v_pk_fma_f32 v[84:85], v[82:83], v[174:175], v[180:181]
	v_pk_fma_f32 v[82:83], v[238:239], v[178:179], v[176:177]
	s_branch .LBB0_656
.Lnear_b0:
	v_add_f32_e32 v0, 1.0, v134
	v_pk_add_f32 v[66:67], v[134:135], s[6:7] op_sel_hi:[0,1]
	v_pk_add_f32 v[68:69], v[134:135], s[8:9] op_sel_hi:[0,1]
	v_pk_add_f32 v[70:71], v[134:135], s[10:11] op_sel_hi:[0,1]
	v_pk_add_f32 v[72:73], v[134:135], s[12:13] op_sel_hi:[0,1]
	v_pk_add_f32 v[74:75], v[134:135], s[14:15] op_sel_hi:[0,1]
	v_pk_add_f32 v[76:77], v[134:135], s[16:17] op_sel_hi:[0,1]
	v_pk_add_f32 v[78:79], v[134:135], s[18:19] op_sel_hi:[0,1]
	v_and_b32_e32 v67, 0x7fffffff, v67
	v_and_b32_e32 v66, 0x7fffffff, v66
	v_and_b32_e32 v69, 0x7fffffff, v69
	v_and_b32_e32 v68, 0x7fffffff, v68
	v_and_b32_e32 v71, 0x7fffffff, v71
	v_and_b32_e32 v70, 0x7fffffff, v70
	v_and_b32_e32 v73, 0x7fffffff, v73
	v_and_b32_e32 v72, 0x7fffffff, v72
	v_and_b32_e32 v75, 0x7fffffff, v75
	v_and_b32_e32 v74, 0x7fffffff, v74
	v_and_b32_e32 v77, 0x7fffffff, v77
	v_and_b32_e32 v76, 0x7fffffff, v76
	v_and_b32_e32 v79, 0x7fffffff, v79
	v_and_b32_e32 v78, 0x7fffffff, v78
	v_and_b32_e32 v136, 0x7fffffff, v134
	v_and_b32_e32 v137, 0x7fffffff, v0
	v_mov_b32_e32 v175, v174
	v_pk_fma_f32 v[80:81], v[78:79], v[174:175], v[192:193]
	v_pk_fma_f32 v[78:79], v[76:77], v[174:175], v[190:191]
	v_pk_fma_f32 v[76:77], v[74:75], v[174:175], v[188:189]
	v_pk_fma_f32 v[74:75], v[72:73], v[174:175], v[186:187]
	v_pk_fma_f32 v[72:73], v[70:71], v[174:175], v[184:185]
	v_pk_fma_f32 v[70:71], v[68:69], v[174:175], v[182:183]
	v_pk_fma_f32 v[68:69], v[66:67], v[174:175], v[180:181]
	v_pk_fma_f32 v[66:67], v[136:137], v[178:179], v[176:177]
	v_cndmask_b32_e64 v0, -v210, v210, s[44:45]
	s_branch .LBB0_673
.Lnear_a1:
	v_add_f32_e32 v96, 1.0, v114
	v_pk_add_f32 v[82:83], v[114:115], s[6:7] op_sel_hi:[0,1]
	v_pk_add_f32 v[84:85], v[114:115], s[8:9] op_sel_hi:[0,1]
	v_pk_add_f32 v[86:87], v[114:115], s[10:11] op_sel_hi:[0,1]
	v_pk_add_f32 v[88:89], v[114:115], s[12:13] op_sel_hi:[0,1]
	v_pk_add_f32 v[90:91], v[114:115], s[14:15] op_sel_hi:[0,1]
	v_pk_add_f32 v[92:93], v[114:115], s[16:17] op_sel_hi:[0,1]
	v_pk_add_f32 v[94:95], v[114:115], s[18:19] op_sel_hi:[0,1]
	v_and_b32_e32 v83, 0x7fffffff, v83
	v_and_b32_e32 v82, 0x7fffffff, v82
	v_and_b32_e32 v85, 0x7fffffff, v85
	v_and_b32_e32 v84, 0x7fffffff, v84
	v_and_b32_e32 v87, 0x7fffffff, v87
	v_and_b32_e32 v86, 0x7fffffff, v86
	v_and_b32_e32 v89, 0x7fffffff, v89
	v_and_b32_e32 v88, 0x7fffffff, v88
	v_and_b32_e32 v91, 0x7fffffff, v91
	v_and_b32_e32 v90, 0x7fffffff, v90
	v_and_b32_e32 v93, 0x7fffffff, v93
	v_and_b32_e32 v92, 0x7fffffff, v92
	v_and_b32_e32 v95, 0x7fffffff, v95
	v_and_b32_e32 v94, 0x7fffffff, v94
	v_and_b32_e32 v116, 0x7fffffff, v114
	v_and_b32_e32 v117, 0x7fffffff, v96
	v_mov_b32_e32 v175, v174
	v_pk_fma_f32 v[96:97], v[94:95], v[174:175], v[192:193]
	v_pk_fma_f32 v[94:95], v[92:93], v[174:175], v[190:191]
	v_pk_fma_f32 v[92:93], v[90:91], v[174:175], v[188:189]
	v_pk_fma_f32 v[90:91], v[88:89], v[174:175], v[186:187]
	v_pk_fma_f32 v[88:89], v[86:87], v[174:175], v[184:185]
	v_pk_fma_f32 v[86:87], v[84:85], v[174:175], v[182:183]
	v_pk_fma_f32 v[84:85], v[82:83], v[174:175], v[180:181]
	v_pk_fma_f32 v[82:83], v[116:117], v[178:179], v[176:177]
	s_branch .LBB0_669
.Lnear_a0:
	v_add_f32_e32 v0, 1.0, v82
	v_pk_add_f32 v[66:67], v[82:83], s[6:7] op_sel_hi:[0,1]
	v_pk_add_f32 v[68:69], v[82:83], s[8:9] op_sel_hi:[0,1]
	v_pk_add_f32 v[70:71], v[82:83], s[10:11] op_sel_hi:[0,1]
	v_pk_add_f32 v[72:73], v[82:83], s[12:13] op_sel_hi:[0,1]
	v_pk_add_f32 v[74:75], v[82:83], s[14:15] op_sel_hi:[0,1]
	v_pk_add_f32 v[76:77], v[82:83], s[16:17] op_sel_hi:[0,1]
	v_pk_add_f32 v[78:79], v[82:83], s[18:19] op_sel_hi:[0,1]
	v_and_b32_e32 v67, 0x7fffffff, v67
	v_and_b32_e32 v66, 0x7fffffff, v66
	v_and_b32_e32 v69, 0x7fffffff, v69
	v_and_b32_e32 v68, 0x7fffffff, v68
	v_and_b32_e32 v71, 0x7fffffff, v71
	v_and_b32_e32 v70, 0x7fffffff, v70
	v_and_b32_e32 v73, 0x7fffffff, v73
	v_and_b32_e32 v72, 0x7fffffff, v72
	v_and_b32_e32 v75, 0x7fffffff, v75
	v_and_b32_e32 v74, 0x7fffffff, v74
	v_and_b32_e32 v77, 0x7fffffff, v77
	v_and_b32_e32 v76, 0x7fffffff, v76
	v_and_b32_e32 v79, 0x7fffffff, v79
	v_and_b32_e32 v78, 0x7fffffff, v78
	v_and_b32_e32 v84, 0x7fffffff, v82
	v_and_b32_e32 v85, 0x7fffffff, v0
	v_mov_b32_e32 v175, v174
	v_pk_fma_f32 v[80:81], v[78:79], v[174:175], v[192:193]
	v_pk_fma_f32 v[78:79], v[76:77], v[174:175], v[190:191]
	v_pk_fma_f32 v[76:77], v[74:75], v[174:175], v[188:189]
	v_pk_fma_f32 v[74:75], v[72:73], v[174:175], v[186:187]
	v_pk_fma_f32 v[72:73], v[70:71], v[174:175], v[184:185]
	v_pk_fma_f32 v[70:71], v[68:69], v[174:175], v[182:183]
	v_pk_fma_f32 v[68:69], v[66:67], v[174:175], v[180:181]
	v_pk_fma_f32 v[66:67], v[84:85], v[178:179], v[176:177]
	v_cndmask_b32_e64 v0, -v210, v210, s[44:45]
	s_branch .LBB0_665
